# scan producer: (x+x)*log2e and -0.6065*log2e constant multiplies folded into single multiplies (16 fewer VALU per chunk)
# speedup vs baseline: 1.0125x; 1.0027x over previous
; __device__ __forceinline__ unsigned cvt_pk_bf16(float lo, float hi) { unsigned r; asm("v_cvt_pk_bf16_f32 %0, %1, %2" : "=v"(r) : "v"(lo), "v"(hi)); return r; }
; __device__ __forceinline__ float bf_lo(unsigned u) { return __uint_as_float(u << 16); }
; __device__ __forceinline__ float bf_hi(unsigned u) { return __uint_as_float(u & 0xffff0000u); }
; __device__ void rw_scan(const Params& p, int l, unsigned char* shm, int item) {
;     ...
;                 for (int g = 0; g < 5; ++g) { const unsigned cu[4] = {rc[g].x, rc[g].y, rc[g].z, rc[g].w};
; #pragma unroll
;                     for (int e = 0; e < 4; ++e) { zs[g][2 * e] = bf_lo(cu[e]); zs[g][2 * e + 1] = bf_hi(cu[e]); } }
; #pragma unroll
;                 for (int e = 0; e < 8; ++e) { rs_[e] = zs[0][e]; ks_[e] = zs[1][e]; vs_[e] = zs[2][e]; }
;                 u32x4 tw4, ad4;
;                 tw4.x = cvt_pk_bf16(tanhf_(zs[3][0]), tanhf_(zs[3][1])); tw4.y = cvt_pk_bf16(tanhf_(zs[3][2]), tanhf_(zs[3][3])); tw4.z = cvt_pk_bf16(tanhf_(zs[3][4]), tanhf_(zs[3][5])); tw4.w = cvt_pk_bf16(tanhf_(zs[3][6]), tanhf_(zs[3][7]));
;                 ad4.x = cvt_pk_bf16(zs[4][0], zs[4][1]); ad4.y = cvt_pk_bf16(zs[4][2], zs[4][3]); ad4.z = cvt_pk_bf16(zs[4][4], zs[4][5]); ad4.w = cvt_pk_bf16(zs[4][6], zs[4][7]);
;                 *(u32x4*)(twb + ptok * 128 + sub * 16) = tw4; *(u32x4*)(adb + ptok * 128 + sub * 16) = ad4;
;             }
;             if (cn + 1 < T / TC) RW_ISSUE(cn + 1);
;             {
;                 const int arow = ((pw * 8 + r_) & 31) * 128;
;                 bf16x8 aw[2], aa_[2];
; #pragma unroll
;                 for (int ks2 = 0; ks2 < 2; ++ks2) { aw[ks2] = *(const bf16x8*)(twb + arow + ks2 * 64 + kg * 16); aa_[ks2] = *(const bf16x8*)(adb + arow + ks2 * 64 + kg * 16); }
; #pragma unroll
;                 for (int nt = 0; nt < 4; ++nt) {
;                     f32x4 cw = (f32x4){0.f, 0.f, 0.f, 0.f}, ca = (f32x4){0.f, 0.f, 0.f, 0.f};
; #pragma unroll
;                     for (int ks2 = 0; ks2 < 2; ++ks2) { cw = __builtin_amdgcn_mfma_f32_16x16x32_bf16(aw[ks2], bfr[0][nt][ks2], cw, 0, 0, 0); ca = __builtin_amdgcn_mfma_f32_16x16x32_bf16(aa_[ks2], bfr[1][nt][ks2], ca, 0, 0, 0); }
;                     if (kg < 2) {
; #pragma unroll
;                         for (int i = 0; i < 4; ++i) { wl[(4 * kg + i) * 64 + 16 * nt + r_] = cw[i]; al[(4 * kg + i) * 64 + 16 * nt + r_] = ca[i]; } }
.LBB0_308:
	s_waitcnt vmcnt(1)
	v_lshlrev_b32_e32 v2, 16, v86
	v_and_b32_e32 v3, 0xffff0000, v86
	v_mul_f32_e32 v2, 0x4038aa3b, v2
	v_mul_f32_e32 v3, 0x4038aa3b, v3
	v_exp_f32_e32 v2, v2
	v_exp_f32_e32 v3, v3
	v_lshlrev_b32_e32 v4, 16, v87
	v_add_f32_e32 v2, 1.0, v2
	v_add_f32_e32 v3, 1.0, v3
	v_rcp_f32_e32 v2, v2
	v_rcp_f32_e32 v3, v3
	v_mul_f32_e32 v4, 0x4038aa3b, v4
	v_exp_f32_e32 v4, v4
	v_and_b32_e32 v5, 0xffff0000, v87
	v_fma_f32 v2, v2, -2.0, 1.0
	v_fma_f32 v3, v3, -2.0, 1.0
	v_lshlrev_b32_e32 v74, 16, v88
	v_cvt_pk_bf16_f32 v2, v2, v3
	v_add_f32_e32 v3, 1.0, v4
	v_mul_f32_e32 v4, 0x4038aa3b, v5
	v_exp_f32_e32 v4, v4
	v_mul_f32_e32 v5, 0x4038aa3b, v74
	v_exp_f32_e32 v5, v5
	v_and_b32_e32 v75, 0xffff0000, v88
	v_add_f32_e32 v4, 1.0, v4
	v_rcp_f32_e32 v3, v3
	v_rcp_f32_e32 v4, v4
	v_add_f32_e32 v5, 1.0, v5
	v_mul_f32_e32 v74, 0x4038aa3b, v75
	v_rcp_f32_e32 v5, v5
	v_exp_f32_e32 v74, v74
	v_lshlrev_b32_e32 v76, 16, v89
	v_fma_f32 v3, v3, -2.0, 1.0
	v_fma_f32 v4, v4, -2.0, 1.0
	v_and_b32_e32 v77, 0xffff0000, v89
	v_cvt_pk_bf16_f32 v3, v3, v4
	v_fma_f32 v4, v5, -2.0, 1.0
	v_add_f32_e32 v5, 1.0, v74
	v_mul_f32_e32 v74, 0x4038aa3b, v76
	v_exp_f32_e32 v74, v74
	v_mul_f32_e32 v75, 0x4038aa3b, v77
	v_exp_f32_e32 v75, v75
	v_rcp_f32_e32 v5, v5
	v_add_f32_e32 v74, 1.0, v74
	v_rcp_f32_e32 v74, v74
	v_add_f32_e32 v75, 1.0, v75
	v_rcp_f32_e32 v75, v75
	v_fma_f32 v5, v5, -2.0, 1.0
	v_cvt_pk_bf16_f32 v4, v4, v5
	v_fma_f32 v5, v74, -2.0, 1.0
	v_add_u32_e32 v192, s16, v190
	v_fma_f32 v74, v75, -2.0, 1.0
	v_cvt_pk_bf16_f32 v5, v5, v74
	s_waitcnt vmcnt(0)
	v_lshlrev_b32_e32 v78, 16, v82
	v_and_b32_e32 v79, 0xffff0000, v82
	v_lshlrev_b32_e32 v80, 16, v83
	v_and_b32_e32 v81, 0xffff0000, v83
	v_lshlrev_b32_e32 v82, 16, v84
	v_and_b32_e32 v83, 0xffff0000, v84
	v_lshlrev_b32_e32 v84, 16, v85
	v_and_b32_e32 v85, 0xffff0000, v85
	v_cvt_pk_bf16_f32 v74, v78, v79
	v_cvt_pk_bf16_f32 v75, v80, v81
	v_cvt_pk_bf16_f32 v76, v82, v83
	v_cvt_pk_bf16_f32 v77, v84, v85
	ds_write_b128 v189, v[2:5]
	ds_write_b128 v188, v[74:77]
	v_cndmask_b32_e32 v2, v191, v192, vcc
	v_add_u32_e32 v4, s14, v2
	v_and_b32_e32 v74, 0x7f, v2
	v_mov_b64_e32 v[2:3], s[94:95]
	v_mad_i64_i32 v[2:3], s[0:1], v4, s22, v[2:3]
	s_mov_b64 s[0:1], 0xe504c00
	s_nop 0
	v_lshl_add_u64 v[2:3], v[2:3], 0, s[0:1]
	s_movk_i32 s0, 0x7f
	v_cmp_eq_u32_e64 s[0:1], s0, v74
	v_readlane_b32 s8, v253, 20
	v_ashrrev_i32_e32 v4, 6, v4
	v_cndmask_b32_e64 v5, 0, 1, s[0:1]
	v_readlane_b32 s9, v253, 21
	v_and_or_b32 v75, v4, -2, v5
	ds_read_b128 v[94:97], v187
	ds_read_b128 v[102:105], v186
	v_mov_b64_e32 v[4:5], s[8:9]
	s_movk_i32 s8, 0x1500
	v_mad_i64_i32 v[4:5], s[8:9], v75, s8, v[4:5]
	v_cmp_eq_u32_e64 s[8:9], 0, v74
	s_or_b64 s[0:1], s[8:9], s[0:1]
	v_cndmask_b32_e64 v115, v3, v5, s[0:1]
	v_cndmask_b32_e64 v114, v2, v4, s[0:1]
	v_lshl_add_u64 v[2:3], v[126:127], 1, v[114:115]
	v_lshl_add_u64 v[4:5], v[128:129], 1, v[114:115]
	global_load_dwordx4 v[78:81], v[2:3], off
	global_load_dwordx4 v[74:77], v[4:5], off
	ds_read_b128 v[106:109], v187 offset:64
	ds_read_b128 v[110:113], v186 offset:64
	s_waitcnt lgkmcnt(3)
	v_mfma_f32_16x16x32_bf16 v[82:85], v[94:97], v[62:65], 0
	v_mov_b32_e32 v145, v1
	v_lshl_add_u64 v[2:3], v[142:143], 1, v[114:115]
	v_lshl_add_u64 v[86:87], v[114:115], 0, v[0:1]
	v_lshl_add_u64 v[122:123], v[114:115], 0, v[144:145]
	global_load_dwordx4 v[2:5], v[2:3], off
	s_nop 0
	global_load_dwordx4 v[86:89], v[86:87], off
	s_waitcnt lgkmcnt(1)
	v_mfma_f32_16x16x32_bf16 v[114:117], v[106:109], v[58:61], v[82:85]
	s_nop 2
	global_load_dwordx4 v[82:85], v[122:123], off
	v_mfma_f32_16x16x32_bf16 v[118:121], v[102:105], v[66:69], 0
	s_waitcnt lgkmcnt(0)
	v_mfma_f32_16x16x32_bf16 v[118:121], v[110:113], v[54:57], v[118:121]
	s_and_saveexec_b64 s[0:1], s[6:7]
	s_cbranch_execz .LBB0_310
	ds_write2st64_b32 v185, v114, v115 offset1:1
	s_nop 4
	ds_write2st64_b32 v185, v118, v119 offset0:8 offset1:9
	ds_write2st64_b32 v185, v116, v117 offset0:2 offset1:3
	ds_write2st64_b32 v185, v120, v121 offset0:10 offset1:11

; __device__ __forceinline__ float sigmoidf_(float x) { return __builtin_amdgcn_rcpf(1.0f + __expf(-x)); }
; __device__ __forceinline__ float allreduce8(float x) { x += dppf(x, 0); x += dppf(x, 1); x += dppf(x, 2); return x; }
; __device__ void rw_scan(const Params& p, int l, unsigned char* shm, int item) {
;     ...
;             {
;                 const int tl = lane >> 3;
;                 const f32x4 wl0 = *(const f32x4*)(wl + tl * 64 + sub * 8), wl1 = *(const f32x4*)(wl + tl * 64 + sub * 8 + 4), al0 = *(const f32x4*)(al + tl * 64 + sub * 8), al1 = *(const f32x4*)(al + tl * 64 + sub * 8 + 4);
;                 float kkv[8], ssq = 0.f, av[8], dec[8], kd[8], bpart = 0.f;
; #pragma unroll
;                 for (int e = 0; e < 8; ++e) { const float wa = cst[sub * 8 + e] + (e < 4 ? wl0[e & 3] : wl1[e & 3]), aa = cst[64 + sub * 8 + e] + (e < 4 ? al0[e & 3] : al1[e & 3]);
;                     av[e] = sigmoidf_(aa); dec[e] = __expf(-0.6065306597126334f * sigmoidf_(wa)); kkv[e] = ks_[e] * cst[128 + sub * 8 + e]; ssq += kkv[e] * kkv[e];
;                     kd[e] = ks_[e] * (1.0f + (av[e] - 1.0f) * cst[192 + sub * 8 + e]); bpart += rs_[e] * kd[e] * cst[256 + sub * 8 + e]; }
;                 ssq = allreduce8(ssq); bpart = allreduce8(bpart);
.LBB0_316:
	s_or_b64 exec, exec, s[0:1]
	v_lshlrev_b32_e32 v146, 16, v98
	v_and_b32_e32 v147, 0xffff0000, v98
	v_lshlrev_b32_e32 v148, 16, v99
	v_and_b32_e32 v149, 0xffff0000, v99
	v_lshlrev_b32_e32 v158, 16, v100
	v_and_b32_e32 v159, 0xffff0000, v100
	v_lshlrev_b32_e32 v156, 16, v101
	v_and_b32_e32 v157, 0xffff0000, v101
	ds_read_b128 v[98:101], v184
	ds_read_b128 v[106:109], v184 offset:16
	ds_read_b128 v[102:105], v184 offset:2048
	ds_read_b128 v[110:113], v184 offset:2064
	v_lshlrev_b32_e32 v94, 16, v90
	s_waitcnt lgkmcnt(0)
	v_add_f32_e32 v102, v102, v214
	v_mul_f32_e32 v102, 0xbfb8aa3b, v102
	v_exp_f32_e32 v102, v102
	v_add_f32_e32 v104, v104, v216
	v_mul_f32_e32 v104, 0xbfb8aa3b, v104
	v_exp_f32_e32 v104, v104
	v_add_f32_e32 v102, 1.0, v102
	v_rcp_f32_e32 v150, v102
	v_add_f32_e32 v102, v103, v215
	v_mul_f32_e32 v102, 0xbfb8aa3b, v102
	v_exp_f32_e32 v102, v102
	v_add_f32_e32 v98, v98, v206
	v_add_f32_e32 v104, 1.0, v104
	v_and_b32_e32 v95, 0xffff0000, v90
	v_add_f32_e32 v102, 1.0, v102
	v_rcp_f32_e32 v151, v102
	v_add_f32_e32 v106, v106, v210
	v_add_f32_e32 v108, v108, v212
	v_lshlrev_b32_e32 v96, 16, v91
	v_pk_add_f32 v[102:103], v[150:151], -1.0 op_sel_hi:[1,0]
	v_add_f32_e32 v107, v107, v211
	s_waitcnt lgkmcnt(2)
	v_pk_fma_f32 v[102:103], v[230:231], v[102:103], 1.0 op_sel_hi:[1,1,0]
	v_and_b32_e32 v97, 0xffff0000, v91
	v_pk_mul_f32 v[102:103], v[102:103], v[146:147]
	v_add_f32_e32 v109, v109, v213
	v_mul_f32_e32 v118, v102, v94
	s_waitcnt lgkmcnt(1)
	v_fma_f32 v145, v238, v118, 0
	v_rcp_f32_e32 v152, v104
	v_add_f32_e32 v104, v105, v217
	v_mul_f32_e32 v104, 0xbfb8aa3b, v104
	v_exp_f32_e32 v104, v104
	v_mul_f32_e32 v118, v103, v95
	v_fmac_f32_e32 v145, v239, v118
	v_add_f32_e32 v104, 1.0, v104
	v_rcp_f32_e32 v153, v104
	v_add_f32_e32 v99, v99, v207
	v_add_f32_e32 v100, v100, v208
	v_add_f32_e32 v101, v101, v209
	v_pk_add_f32 v[104:105], v[152:153], -1.0 op_sel_hi:[1,0]
	v_lshlrev_b32_e32 v90, 16, v92
	v_pk_fma_f32 v[104:105], v[232:233], v[104:105], 1.0 op_sel_hi:[1,1,0]
	s_waitcnt lgkmcnt(1)
	v_add_f32_e32 v110, v110, v218
	v_mul_f32_e32 v110, 0xbfb8aa3b, v110
	v_exp_f32_e32 v110, v110
	v_add_f32_e32 v112, v112, v220
	v_mul_f32_e32 v112, 0xbfb8aa3b, v112
	v_exp_f32_e32 v112, v112
	v_add_f32_e32 v110, 1.0, v110
	v_rcp_f32_e32 v114, v110
	v_add_f32_e32 v110, v111, v219
	v_mul_f32_e32 v110, 0xbfb8aa3b, v110
	v_add_f32_e32 v112, 1.0, v112
	v_exp_f32_e32 v110, v110
	v_rcp_f32_e32 v116, v112
	v_add_f32_e32 v112, v113, v221
	v_mul_f32_e32 v112, 0xbfb8aa3b, v112
	v_exp_f32_e32 v112, v112
	v_add_f32_e32 v110, 1.0, v110
	v_pk_mul_f32 v[104:105], v[104:105], v[148:149]
	v_rcp_f32_e32 v115, v110
	v_mul_f32_e32 v118, v104, v96
	v_add_f32_e32 v112, 1.0, v112
	v_fmac_f32_e32 v145, v240, v118
	v_mul_f32_e32 v118, v105, v97
	v_rcp_f32_e32 v117, v112
	v_fmac_f32_e32 v145, v241, v118
	v_pk_add_f32 v[110:111], v[114:115], -1.0 op_sel_hi:[1,0]
	v_pk_add_f32 v[112:113], v[116:117], -1.0 op_sel_hi:[1,0]
	v_pk_fma_f32 v[110:111], v[234:235], v[110:111], 1.0 op_sel_hi:[1,1,0]
	v_and_b32_e32 v91, 0xffff0000, v92
	v_pk_mul_f32 v[110:111], v[110:111], v[158:159]
	s_waitcnt lgkmcnt(1)
	v_pk_mul_f32 v[122:123], v[226:227], v[158:159]
	v_mul_f32_e32 v158, v110, v90
	v_pk_fma_f32 v[112:113], v[236:237], v[112:113], 1.0 op_sel_hi:[1,1,0]
	v_lshlrev_b32_e32 v92, 16, v93
	s_waitcnt lgkmcnt(0)
	v_fmac_f32_e32 v145, v242, v158
	v_mul_f32_e32 v118, v111, v91
	v_pk_mul_f32 v[112:113], v[112:113], v[156:157]
	v_fmac_f32_e32 v145, v243, v118
	v_pk_mul_f32 v[118:119], v[228:229], v[156:157]
	v_mul_f32_e32 v156, v112, v92
	v_fmac_f32_e32 v145, v244, v156
	v_and_b32_e32 v93, 0xffff0000, v93
	v_mul_f32_e32 v120, v113, v93
	v_fmac_f32_e32 v145, v245, v120
	v_pk_mul_f32 v[154:155], v[122:123], v[122:123]
	s_waitcnt lgkmcnt(0)
; __device__ __forceinline__ float sigmoidf_(float x) { return __builtin_amdgcn_rcpf(1.0f + __expf(-x)); }
; __device__ __forceinline__ float allreduce8(float x) { x += dppf(x, 0); x += dppf(x, 1); x += dppf(x, 2); return x; }
; __device__ void rw_scan(const Params& p, int l, unsigned char* shm, int item) {
;     ...
; #pragma unroll
;                 for (int e = 0; e < 8; ++e) { const float wa = cst[sub * 8 + e] + (e < 4 ? wl0[e & 3] : wl1[e & 3]), aa = cst[64 + sub * 8 + e] + (e < 4 ? al0[e & 3] : al1[e & 3]);
;                     av[e] = sigmoidf_(aa); dec[e] = __expf(-0.6065306597126334f * sigmoidf_(wa)); kkv[e] = ks_[e] * cst[128 + sub * 8 + e]; ssq += kkv[e] * kkv[e];
;                     kd[e] = ks_[e] * (1.0f + (av[e] - 1.0f) * cst[192 + sub * 8 + e]); bpart += rs_[e] * kd[e] * cst[256 + sub * 8 + e]; }
;                 ssq = allreduce8(ssq); bpart = allreduce8(bpart);
;                 const float inrm = __builtin_amdgcn_rcpf(fmaxf(__builtin_amdgcn_sqrtf(ssq), 1e-12f));
; #pragma unroll
;                 for (int hf = 0; hf < 2; ++hf) {
;                     f32x4 o_r, o_w, o_k, o_a, o_b;
; #pragma unroll
;                     for (int e = 0; e < 4; ++e) { const int ee = hf * 4 + e; const float kk = kkv[ee] * inrm; o_r[e] = rs_[ee]; o_w[e] = dec[ee]; o_k[e] = kd[ee]; o_a[e] = -kk; o_b[e] = kk * av[ee]; }
;                     const int o = ptok * 64 + sub * 8 + hf * 4;
;                     *(f32x4*)(sr + o) = o_r; *(f32x4*)(sw + o) = o_w; *(f32x4*)(sk + o) = o_k; *(f32x4*)(sa + o) = o_a; *(f32x4*)(sb + o) = o_b;
;                 }
;                 if ((sub >> 1) == quarter) { const int o = ptok * 16 + (sub & 1) * 8;
;                     *(f32x4*)(sv + o) = (f32x4){vs_[0], vs_[1], vs_[2], vs_[3]}; *(f32x4*)(sv + o + 4) = (f32x4){vs_[4], vs_[5], vs_[6], vs_[7]}; }
	v_pk_mul_f32 v[146:147], v[222:223], v[146:147]
	v_pk_mul_f32 v[148:149], v[224:225], v[148:149]
	v_pk_mul_f32 v[156:157], v[146:147], v[146:147]
	v_add_f32_dpp v120, v145, v145 quad_perm:[1,0,3,2] row_mask:0xf bank_mask:0xf bound_ctrl:1
	v_pk_mul_f32 v[158:159], v[148:149], v[148:149]
	v_add_f32_e32 v145, v156, v157
	v_add_f32_e32 v145, v145, v158
	v_add_f32_e32 v145, v145, v159
	v_add_f32_e32 v145, v145, v154
	v_pk_mul_f32 v[124:125], v[118:119], v[118:119]
	v_add_f32_e32 v145, v145, v155
	v_mul_f32_e32 v98, 0xbfb8aa3b, v98
	v_mul_f32_e32 v99, 0xbfb8aa3b, v99
	v_mul_f32_e32 v100, 0xbfb8aa3b, v100
	v_mul_f32_e32 v101, 0xbfb8aa3b, v101
	v_add_f32_e32 v124, v145, v124
	v_exp_f32_e32 v98, v98
	v_exp_f32_e32 v99, v99
	v_exp_f32_e32 v100, v100
	v_exp_f32_e32 v101, v101
	v_mul_f32_e32 v106, 0xbfb8aa3b, v106
	v_mul_f32_e32 v107, 0xbfb8aa3b, v107
	v_mul_f32_e32 v108, 0xbfb8aa3b, v108
	v_mul_f32_e32 v109, 0xbfb8aa3b, v109
	v_add_f32_e32 v124, v124, v125
	v_exp_f32_e32 v106, v106
	v_exp_f32_e32 v107, v107
	v_exp_f32_e32 v108, v108
	v_exp_f32_e32 v109, v109
	v_add_f32_dpp v124, v124, v124 quad_perm:[1,0,3,2] row_mask:0xf bank_mask:0xf bound_ctrl:1
	v_add_f32_e32 v98, 1.0, v98
	v_add_f32_e32 v99, 1.0, v99
	v_add_f32_dpp v124, v124, v124 quad_perm:[2,3,0,1] row_mask:0xf bank_mask:0xf bound_ctrl:1
	v_add_f32_e32 v100, 1.0, v100
	v_add_f32_e32 v101, 1.0, v101
	v_add_f32_dpp v124, v124, v124 row_half_mirror row_mask:0xf bank_mask:0xf bound_ctrl:1
	v_sqrt_f32_e32 v124, v124
	v_rcp_f32_e32 v98, v98
	v_rcp_f32_e32 v99, v99
	v_rcp_f32_e32 v100, v100
	v_rcp_f32_e32 v101, v101
	v_add_f32_e32 v106, 1.0, v106
	v_add_f32_e32 v107, 1.0, v107
	v_add_f32_e32 v108, 1.0, v108
	v_add_f32_e32 v109, 1.0, v109
	v_rcp_f32_e32 v106, v106
	v_rcp_f32_e32 v107, v107
	v_rcp_f32_e32 v108, v108
	v_rcp_f32_e32 v109, v109
	v_max_f32_e32 v124, 0x2b8cbccc, v124
	v_mul_f32_e32 v98, 0xbf60028a, v98
	v_mul_f32_e32 v99, 0xbf60028a, v99
	v_mul_f32_e32 v100, 0xbf60028a, v100
	v_mul_f32_e32 v101, 0xbf60028a, v101
	v_rcp_f32_e32 v124, v124
	s_bitcmp1_b32 s15, 0
	v_mul_f32_e32 v106, 0xbf60028a, v106
	v_mul_f32_e32 v107, 0xbf60028a, v107
	v_mul_f32_e32 v108, 0xbf60028a, v108
	v_mul_f32_e32 v109, 0xbf60028a, v109
	s_cselect_b32 s0, 0xa800, 0
	v_exp_f32_e32 v98, v98
	v_exp_f32_e32 v99, v99
	v_exp_f32_e32 v100, v100
	v_exp_f32_e32 v101, v101
	s_add_i32 s8, s0, 0
	v_exp_f32_e32 v106, v106
	v_exp_f32_e32 v107, v107
	v_exp_f32_e32 v108, v108
	v_exp_f32_e32 v109, v109
	v_add_f32_dpp v120, v120, v120 quad_perm:[2,3,0,1] row_mask:0xf bank_mask:0xf bound_ctrl:1
	v_pk_mul_f32 v[154:155], v[146:147], v[124:125] op_sel_hi:[1,0]
	v_pk_mul_f32 v[156:157], v[148:149], v[124:125] op_sel_hi:[1,0]
	v_lshl_add_u32 v125, v182, 2, s8
	v_mov_b32_dpp v121, v120 row_half_mirror row_mask:0xf bank_mask:0xf bound_ctrl:1
	v_xor_b32_e32 v147, 0x80000000, v155
	v_xor_b32_e32 v146, 0x80000000, v154
	v_xor_b32_e32 v148, 0x80000000, v156
	v_xor_b32_e32 v149, 0x80000000, v157
	v_pk_mul_f32 v[150:151], v[150:151], v[154:155]
	v_pk_mul_f32 v[152:153], v[152:153], v[156:157]
	ds_write_b128 v125, v[94:97]
	ds_write_b128 v125, v[98:101] offset:8192
	ds_write_b128 v125, v[102:105] offset:16384
	ds_write_b128 v125, v[146:149] offset:24576
	ds_write_b128 v125, v[150:153] offset:32768
	v_pk_mul_f32 v[98:99], v[122:123], v[124:125] op_sel_hi:[1,0]
	v_pk_mul_f32 v[100:101], v[118:119], v[124:125] op_sel_hi:[1,0]
	v_xor_b32_e32 v95, 0x80000000, v99
	v_xor_b32_e32 v94, 0x80000000, v98
	v_xor_b32_e32 v96, 0x80000000, v100
	v_xor_b32_e32 v97, 0x80000000, v101
	v_pk_mul_f32 v[98:99], v[114:115], v[98:99]
	v_pk_mul_f32 v[100:101], v[116:117], v[100:101]
	ds_write_b128 v125, v[90:93] offset:16
	ds_write_b128 v125, v[106:109] offset:8208
	ds_write_b128 v125, v[110:113] offset:16400
	ds_write_b128 v125, v[94:97] offset:24592
	ds_write_b128 v125, v[98:101] offset:32784
	s_and_saveexec_b64 s[0:1], s[4:5]
	s_cbranch_execz .LBB0_318
	v_lshlrev_b32_e32 v94, 2, v181
	v_lshlrev_b32_e32 v90, 16, v70
	v_and_b32_e32 v91, 0xffff0000, v70
	v_lshlrev_b32_e32 v92, 16, v71
	v_and_b32_e32 v93, 0xffff0000, v71
	v_add3_u32 v94, s8, v180, v94
	v_lshlrev_b32_e32 v70, 16, v72
	v_and_b32_e32 v71, 0xffff0000, v72
	v_lshlrev_b32_e32 v72, 16, v73
	v_and_b32_e32 v73, 0xffff0000, v73
	ds_write_b128 v94, v[90:93] offset:40960
	ds_write_b128 v94, v[70:73] offset:40976
